# mlA gate tables up front (grid-size generic: item stride from the grid size, per-workgroup item counter)
# baseline (speedup 1.0000x reference)
.Lmla_g_loop:
	s_lshl_b32 s6, s99, 3
	s_add_u32 s6, s6, s98
	s_mul_i32 s6, s6, s86
	s_add_u32 s6, s6, s82
	s_cmp_ge_u32 s6, 0x880
	s_cbranch_scc1 .Lmla_g_done
	s_mul_hi_i32 s7, s6, 0x78787879
	s_lshr_b32 s8, s7, 31
	s_ashr_i32 s7, s7, 5
	s_add_i32 s7, s7, s8
	s_mul_i32 s8, s7, 0x44
	s_sub_u32 s8, s6, s8
	s_and_b32 s12, s7, 1
	s_lshr_b32 s13, s7, 3
	s_cmp_lt_u32 s8, 4
	s_cselect_b32 s2, 3, 0x43
	s_cselect_b32 s3, 0, 4
	s_sub_u32 s3, s8, s3
	s_sub_u32 s2, s2, s8
	s_cmp_lg_u32 s12, 0
	s_cselect_b32 s2, s2, s3
	s_lshl_b32 s2, s2, 6
	s_lshl_b32 s3, s13, 8
	s_add_u32 s3, s3, 0x4000
	s_lshl_b32 s13, s13, 12
	s_cmp_lt_u32 s8, 4
	s_cselect_b32 s3, s3, s13
	s_add_u32 s2, s2, s3
	v_and_b32_e32 v5, 63, v28
	v_sub_u32_e32 v6, 63, v5
	s_cmp_lg_u32 s12, 0
	s_cselect_b64 vcc, -1, 0
	v_cndmask_b32_e32 v5, v5, v6, vcc
	v_add_u32_e32 v5, s2, v5
	s_movk_i32 s3, 0x3600
	v_mul_lo_u32 v5, v5, s3
	s_bfe_u32 s9, s7, 0x20001
	s_lshl_b32 s3, s12, 3
	s_add_u32 s3, s3, s9
	s_lshl_b32 s3, s3, 1
	s_add_u32 s3, s3, 0x7601d40
	s_add_u32 s2, s88, s3
	s_addc_u32 s3, s89, 0
	s_nop 1
	global_load_ushort v39, v5, s[2:3]
	global_load_ushort v38, v5, s[2:3] offset:8
	s_lshl_b32 s12, s12, 2
	s_or_b32 s9, s9, s12
	v_readlane_b32 s12, v254, 61
	s_nop 3
	s_or_b32 s9, s9, s12
	s_lshl_b32 s9, s9, 2
	s_add_u32 s9, s9, 0x22340
	v_mov_b32_e32 v0, s9
	ds_read_b32 v1, v0 offset:64
	ds_read_b32 v0, v0
	s_mov_b32 s7, 0xbfb8aa3b
	v_mov_b32_e32 v14, 0x7f800000
	s_mul_i32 s8, s6, 0x300
	s_add_u32 s8, s14, s8
	s_waitcnt vmcnt(0) lgkmcnt(0)
	v_lshlrev_b32_e32 v39, 16, v39
	v_lshlrev_b32_e32 v38, 16, v38
	v_add_f32_e32 v0, v39, v0
	v_add_f32_e32 v2, v38, v1
	v_mul_f32_e64 v3, |v2|, s7
	v_fma_f32 v4, |v2|, s7, -v3
	s_mov_b32 s7, 0xb2a5705f
	v_rndne_f32_e32 v5, v3
	v_fma_f32 v4, |v2|, s7, v4
	v_sub_f32_e32 v3, v3, v5
	v_add_f32_e32 v3, v3, v4
	v_exp_f32_e32 v3, v3
	v_cvt_i32_f32_e32 v4, v5
	s_mov_b32 s7, 0x42ce8ed0
	v_cmp_ngt_f32_e64 vcc, |v2|, s7
	s_mov_b32 s7, 0xc2b17218
	v_ldexp_f32 v3, v3, v4
	v_cndmask_b32_e32 v3, 0, v3, vcc
	v_cmp_nlt_f32_e64 vcc, |v2|, s7
	v_min_f32_e32 v1, 0, v2
	s_mov_b32 s7, 0x3f2aaaab
	v_cndmask_b32_e32 v2, v14, v3, vcc
	v_add_f32_e32 v3, 1.0, v2
	v_add_f32_e32 v4, -1.0, v3
	v_sub_f32_e32 v5, v4, v3
	v_add_f32_e32 v5, 1.0, v5
	v_sub_f32_e32 v4, v2, v4
	v_add_f32_e32 v6, v4, v5
	v_frexp_mant_f32_e32 v4, v3
	v_cmp_gt_f32_e32 vcc, s7, v4
	v_cvt_f64_f32_e32 v[4:5], v3
	v_frexp_exp_i32_f64_e32 v4, v[4:5]
	v_subbrev_co_u32_e32 v4, vcc, 0, v4, vcc
	v_sub_u32_e32 v5, 0, v4
	v_ldexp_f32 v3, v3, v5
	v_ldexp_f32 v5, v6, v5
	v_add_f32_e32 v6, -1.0, v3
	v_add_f32_e32 v7, 1.0, v6
	v_sub_f32_e32 v7, v3, v7
	v_add_f32_e32 v7, v5, v7
	v_add_f32_e32 v8, v6, v7
	v_sub_f32_e32 v6, v6, v8
	v_add_f32_e32 v6, v7, v6
	v_add_f32_e32 v7, 1.0, v3
	v_add_f32_e32 v9, -1.0, v7
	v_sub_f32_e32 v3, v3, v9
	v_add_f32_e32 v3, v5, v3
	v_add_f32_e32 v5, v7, v3
	v_sub_f32_e32 v7, v7, v5
	v_add_f32_e32 v3, v3, v7
	v_rcp_f32_e32 v7, v5
	v_cvt_f32_i32_e32 v4, v4
	s_mov_b32 s7, 0x3f317218
	v_mul_f32_e32 v9, v8, v7
	v_mul_f32_e32 v10, v5, v9
	v_fma_f32 v11, v9, v5, -v10
	v_fmac_f32_e32 v11, v9, v3
	v_add_f32_e32 v12, v10, v11
	v_sub_f32_e32 v13, v8, v12
	v_sub_f32_e32 v8, v8, v13
	v_sub_f32_e32 v10, v12, v10
	v_sub_f32_e32 v8, v8, v12
	v_add_f32_e32 v6, v6, v8
	v_sub_f32_e32 v8, v10, v11
	v_add_f32_e32 v6, v8, v6
	v_add_f32_e32 v8, v13, v6
	v_mul_f32_e32 v10, v7, v8
	v_mul_f32_e32 v11, v5, v10
	v_fma_f32 v5, v10, v5, -v11
	v_fmac_f32_e32 v5, v10, v3
	v_sub_f32_e32 v3, v13, v8
	v_add_f32_e32 v3, v6, v3
	v_add_f32_e32 v6, v11, v5
	v_sub_f32_e32 v12, v8, v6
	v_sub_f32_e32 v8, v8, v12
	v_sub_f32_e32 v11, v6, v11
	v_sub_f32_e32 v6, v8, v6
	v_add_f32_e32 v3, v3, v6
	v_sub_f32_e32 v5, v11, v5
	v_add_f32_e32 v3, v5, v3
	v_add_f32_e32 v5, v9, v10
	v_add_f32_e32 v3, v12, v3
	v_sub_f32_e32 v6, v5, v9
	v_mul_f32_e32 v3, v7, v3
	v_sub_f32_e32 v6, v10, v6
	v_add_f32_e32 v3, v6, v3
	v_mul_f32_e32 v9, 0x3f317218, v4
	v_add_f32_e32 v6, v5, v3
	v_fma_f32 v10, v4, s7, -v9
	v_mul_f32_e32 v7, v6, v6
	v_mov_b32_e32 v8, 0x3ecc95a3
	v_fmac_f32_e32 v10, 0xb102e308, v4
	v_sub_f32_e32 v4, v6, v5
	v_fmamk_f32 v8, v7, 0x3e9b6dac, v8
	v_sub_f32_e32 v3, v3, v4
	v_add_f32_e32 v4, v9, v10
	v_fmaak_f32 v8, v7, v8, 0x3f2aaada
	v_sub_f32_e32 v5, v4, v9
	v_ldexp_f32 v9, v6, 1
	v_mul_f32_e32 v6, v6, v7
	v_mul_f32_e32 v6, v6, v8
	v_add_f32_e32 v7, v9, v6
	v_sub_f32_e32 v8, v7, v9
	v_ldexp_f32 v3, v3, 1
	v_sub_f32_e32 v6, v6, v8
	v_add_f32_e32 v3, v3, v6
	v_add_f32_e32 v6, v7, v3
	v_sub_f32_e32 v7, v6, v7
	v_sub_f32_e32 v3, v3, v7
	v_add_f32_e32 v7, v4, v6
	v_sub_f32_e32 v8, v7, v4
	v_sub_f32_e32 v9, v7, v8
	v_sub_f32_e32 v5, v10, v5
	v_sub_f32_e32 v4, v4, v9
	v_sub_f32_e32 v6, v6, v8
	v_add_f32_e32 v4, v6, v4
	v_add_f32_e32 v6, v5, v3
	v_sub_f32_e32 v8, v6, v5
	v_sub_f32_e32 v9, v6, v8
	v_sub_f32_e32 v5, v5, v9
	v_sub_f32_e32 v3, v3, v8
	v_add_f32_e32 v4, v6, v4
	v_add_f32_e32 v3, v3, v5
	v_add_f32_e32 v5, v7, v4
	v_sub_f32_e32 v6, v5, v7
	v_sub_f32_e32 v4, v4, v6
	v_add_f32_e32 v3, v3, v4
	s_mov_b32 s7, 0x7f800000
	v_add_f32_e32 v3, v5, v3
	v_cmp_neq_f32_e32 vcc, s7, v2
	s_mov_b32 s7, 0x33800000
	s_nop 0
	v_cndmask_b32_e32 v3, v14, v3, vcc
	v_cmp_lt_f32_e64 vcc, |v2|, s7
	s_mul_hi_i32 s7, s6, 0x300
	s_addc_u32 s9, s15, s7
	v_cndmask_b32_e32 v2, v3, v2, vcc
	v_sub_f32_e32 v1, v1, v2
	v_mov_b32_e32 v2, v1
	s_nop 1
	v_add_f32_dpp v2, v2, v2 row_shr:1 row_mask:0xf bank_mask:0xf
	s_nop 1
	v_add_f32_dpp v2, v2, v2 row_shr:2 row_mask:0xf bank_mask:0xf
	s_nop 1
	v_add_f32_dpp v2, v2, v2 row_shr:4 row_mask:0xf bank_mask:0xf
	s_nop 1
	v_add_f32_dpp v2, v2, v2 row_shr:8 row_mask:0xf bank_mask:0xf
	s_nop 1
	v_add_f32_dpp v2, v2, v2 row_bcast:15 row_mask:0xa bank_mask:0xf
	s_nop 1
	v_add_f32_dpp v2, v2, v2 row_bcast:31 row_mask:0xc bank_mask:0xf
	s_nop 1
	v_sub_f32_e32 v3, v0, v2
	v_mov_b32_e32 v4, v3
	s_nop 1
	v_max_f32_dpp v4, v4, v4 row_shr:1 row_mask:0xf bank_mask:0xf
	s_nop 1
	v_max_f32_dpp v4, v4, v4 row_shr:2 row_mask:0xf bank_mask:0xf
	s_nop 1
	v_max_f32_dpp v4, v4, v4 row_shr:4 row_mask:0xf bank_mask:0xf
	s_nop 1
	v_max_f32_dpp v4, v4, v4 row_shr:8 row_mask:0xf bank_mask:0xf
	s_nop 1
	v_max_f32_dpp v4, v4, v4 row_bcast:15 row_mask:0xa bank_mask:0xf
	s_nop 1
	v_max_f32_dpp v4, v4, v4 row_bcast:31 row_mask:0xc bank_mask:0xf
	s_nop 1
	v_lshl_add_u64 v[0:1], s[8:9], 0, v[112:113]
	global_store_dword v[0:1], v3, off
	global_store_dword v[0:1], v2, off offset:256
	global_store_dword v[0:1], v4, off offset:512
	v_readlane_b32 s8, v2, 63
	v_readlane_b32 s9, v4, 63
	s_lshl_b32 s10, s99, 3
	s_add_u32 s10, s10, s98
	s_lshl_b32 s2, s10, 8
	s_add_u32 s2, s2, 0x22400
	v_add_u32_e32 v5, s2, v42
	ds_write_b32 v5, v3
	s_mov_b64 s[2:3], exec
	s_and_b64 exec, exec, s[46:47]
	s_ashr_i32 s7, s6, 31
	s_lshl_b64 s[12:13], s[6:7], 3
	s_add_u32 s12, s16, s12
	s_addc_u32 s13, s17, s13
	s_lshl_b32 s10, s10, 2
	s_add_u32 s10, s10, 0x23400
	v_mov_b32_e32 v1, s9
	v_mov_b32_e32 v0, s10
	ds_write_b32 v0, v1
	v_mov_b32_e32 v0, s8
	v_mov_b64_e32 v[2:3], s[12:13]
	global_store_dwordx2 v[2:3], v[0:1], off
	s_mov_b64 exec, s[2:3]
	s_add_u32 s99, s99, 1
	s_cmp_lt_u32 s99, 2
	s_cbranch_scc1 .Lmla_g_loop
.Lmla_g_done:
	s_waitcnt lgkmcnt(0)
	s_barrier
	s_mov_b32 s99, 0
	s_mov_b32 s6, s82
	s_branch .LBB0_735
.LBB0_734:
	s_or_b64 exec, exec, s[8:9]
	s_add_u32 s99, s99, 1
	v_subrev_u32_e32 v52, s19, v52
	v_subrev_u32_e32 v53, s19, v53
	s_andn2_b64 vcc, exec, s[2:3]
	s_mov_b32 s6, s36
	s_waitcnt lgkmcnt(0)
	s_barrier
	s_cbranch_vccz .LBB0_768
.LBB0_735:
	s_and_saveexec_b64 s[2:3], s[44:45]
	s_cbranch_execz .LBB0_738
	s_mov_b32 s7, s99
	s_lshl_b32 s8, s7, 8
	s_add_u32 s8, s8, 0x22400
	v_add_u32_e32 v0, s8, v42
	ds_read_b32 v3, v0
	s_lshl_b32 s8, s7, 2
	s_add_u32 s8, s8, 0x23400
	v_mov_b32_e32 v1, s8
	ds_read_b32 v1, v1
	s_waitcnt lgkmcnt(0)
	ds_write_b32 v42, v3 offset:64512
	s_and_b64 exec, exec, s[46:47]
	s_cbranch_execz .LBB0_738
	v_readlane_b32 s7, v254, 33
	s_nop 3
	v_mov_b32_e32 v0, s7
	ds_write_b32 v0, v1
